# GLA scan sections A/B1 reordered: gate MFMA first, V-tile LDS-DMA issued in its latency shadow, output-tile flush stores issued after the first half of the gate arithmetic
# speedup vs baseline: 1.0031x; 1.0031x over previous
; __device__ __forceinline__ int crow(int r, int hi) { return (r & 3) + 8 * (r >> 2) + 4 * hi; }
; __device__ __forceinline__ int v_st(int k, int c) { const int kk = (k & ~0xC) | ((k & 4) << 1) | ((k & 8) >> 1); return ((kk >> 3) * 4 + (c >> 5)) * 512 + ((kk & 7) * 32 + (c & 31)) * 2; }
; __device__ __forceinline__ void scan_unit(const int unit, const Args& a, unsigned char* lds, const int mk_wid) {
;     ...
;           for (int p = 0; p < 4; ++p) { const int i_ = p * 16 + (t_ >> 5), c8 = t_ & 31; *(bf16x8*)(lds + L_V + (c8 >> 4) * 16384 + v_st(i_, (c8 & 15) * 8)) = vraw[p]; }
;     ...
;           const bf16x8 af = *(const bf16x8*)(lds + L_LR + (tt * 32 + r32) * 32 + hi * 16);
;           const f32x16 z = __builtin_amdgcn_mfma_f32_32x32x16_bf16(af, upf, f32x16{}, 0, 0, 0);
;           float* lw = las + (tt * 32 + 4 * hi) * 128 + ct * 32 + r32;
; #pragma unroll
;           for (int r = 0; r < 16; ++r) { const float zz = z[r] + biasc;
;               lw[crow(r, 0) * 128] = (fminf(zz, 0.f) - __builtin_amdgcn_logf(1.f + __builtin_amdgcn_exp2f(-1.4426950408889634f * fabsf(zz))) * 0.6931471805599453f) * (1.f / 16.f); } }
.Lscan_nolrw:
	s_cmp_lt_i32 s34, 0
	s_cbranch_scc1 .Lscan_noflrd
	ds_read_b128 v[112:115], v253
	ds_read_b128 v[116:119], v253 offset:4096
	ds_read_b128 v[120:123], v253 offset:8192
	ds_read_b128 v[124:127], v253 offset:12288
	s_ashr_i32 s35, s34, 31
	s_lshl_b64 s[26:27], s[34:35], 6
	s_add_u32 s26, s26, s20
	s_addc_u32 s27, s27, s21
	s_add_u32 s26, s26, 0xffffff00
	s_addc_u32 s27, s27, -1
	s_lshl_b64 s[26:27], s[26:27], 11
	s_add_u32 s26, s26, s18
	s_addc_u32 s27, s27, s19
	s_movk_i32 s98, 0x4000
	s_movk_i32 s99, 0xc000
	s_bitcmp1_b32 s8, 0
	s_cselect_b32 s98, s99, s98
	v_add_u32_e32 v165, s98, v252
	v_add_u32_e32 v166, s98, v165
	v_add_u32_e32 v167, s98, v166
.Lscan_noflrd:
	v_mbcnt_lo_u32_b32 v64, -1, 0
	v_mbcnt_hi_u32_b32 v64, -1, v64
	s_nop 0
	v_add_u32_e32 v64, s72, v64
	s_nop 0
	v_and_b32_e32 v68, 31, v64
	v_bfe_u32 v69, v64, 5, 1
	v_lshlrev_b32_e32 v69, 11, v69
	v_lshlrev_b32_e32 v68, 2, v68
	v_add3_u32 v80, s45, v69, v68
	v_mfma_f32_32x32x16_bf16 v[64:79], v[96:99], v[108:111], 0
	v_add_u32_e32 v82, s96, v247
	v_add_u32_e32 v83, s96, v248
	v_add_u32_e32 v84, s96, v249
	v_add_u32_e32 v85, s96, v250
	s_mov_b32 m0, s97
	s_nop 0
	global_load_lds_dwordx4 v82, s[16:17]
	s_add_i32 m0, s97, 0x400
	s_nop 0
	global_load_lds_dwordx4 v83, s[16:17]
	s_add_i32 m0, s97, 0x800
	s_nop 0
	global_load_lds_dwordx4 v84, s[16:17]
	s_add_i32 m0, s97, 0xc00
	s_nop 0
	global_load_lds_dwordx4 v85, s[16:17]
	s_mov_b32 s96, 1.0
	s_mov_b32 s97, 0xbf317218
	s_mov_b32 s98, 0x3db8aa3b
	s_nop 3
	v_pk_add_f32 v[64:65], v[64:65], v[156:157] op_sel_hi:[1,0]
	v_pk_add_f32 v[66:67], v[66:67], v[156:157] op_sel_hi:[1,0]
	v_pk_add_f32 v[68:69], v[68:69], v[156:157] op_sel_hi:[1,0]
	v_pk_add_f32 v[70:71], v[70:71], v[156:157] op_sel_hi:[1,0]
	v_mul_f32_e64 v82, |v64|, s54
	v_mul_f32_e64 v83, |v65|, s54
	v_mul_f32_e64 v84, |v66|, s54
	v_mul_f32_e64 v85, |v67|, s54
	v_mul_f32_e64 v86, |v68|, s54
	v_mul_f32_e64 v87, |v69|, s54
	v_mul_f32_e64 v88, |v70|, s54
	v_mul_f32_e64 v89, |v71|, s54
	v_exp_f32_e32 v82, v82
	v_exp_f32_e32 v83, v83
	v_exp_f32_e32 v84, v84
	v_exp_f32_e32 v85, v85
	v_exp_f32_e32 v86, v86
	v_exp_f32_e32 v87, v87
	v_exp_f32_e32 v88, v88
	v_exp_f32_e32 v89, v89
	v_pk_add_f32 v[82:83], v[82:83], s[96:97] op_sel_hi:[1,0]
	v_pk_add_f32 v[84:85], v[84:85], s[96:97] op_sel_hi:[1,0]
	v_pk_add_f32 v[86:87], v[86:87], s[96:97] op_sel_hi:[1,0]
	v_pk_add_f32 v[88:89], v[88:89], s[96:97] op_sel_hi:[1,0]
	v_log_f32_e32 v82, v82
	v_log_f32_e32 v83, v83
	v_log_f32_e32 v84, v84
	v_log_f32_e32 v85, v85
	v_log_f32_e32 v86, v86
	v_log_f32_e32 v87, v87
	v_log_f32_e32 v88, v88
	v_log_f32_e32 v89, v89
	v_min_f32_e32 v64, 0, v64
	v_min_f32_e32 v65, 0, v65
	v_min_f32_e32 v66, 0, v66
	v_min_f32_e32 v67, 0, v67
	v_min_f32_e32 v68, 0, v68
	v_min_f32_e32 v69, 0, v69
	v_min_f32_e32 v70, 0, v70
	v_min_f32_e32 v71, 0, v71
	v_pk_fma_f32 v[64:65], v[82:83], s[96:97], v[64:65] op_sel:[0,1,0] op_sel_hi:[1,1,1]
	v_pk_fma_f32 v[66:67], v[84:85], s[96:97], v[66:67] op_sel:[0,1,0] op_sel_hi:[1,1,1]
	v_pk_fma_f32 v[68:69], v[86:87], s[96:97], v[68:69] op_sel:[0,1,0] op_sel_hi:[1,1,1]
	v_pk_fma_f32 v[70:71], v[88:89], s[96:97], v[70:71] op_sel:[0,1,0] op_sel_hi:[1,1,1]
	v_pk_mul_f32 v[64:65], v[64:65], s[98:99] op_sel_hi:[1,0]
	v_pk_mul_f32 v[66:67], v[66:67], s[98:99] op_sel_hi:[1,0]
	v_pk_mul_f32 v[68:69], v[68:69], s[98:99] op_sel_hi:[1,0]
	v_pk_mul_f32 v[70:71], v[70:71], s[98:99] op_sel_hi:[1,0]
	s_cmp_lt_i32 s34, 0
	s_cbranch_scc1 .Lscan_noflush
	s_waitcnt lgkmcnt(3)
	global_store_dwordx4 v252, v[112:115], s[26:27]
	s_waitcnt lgkmcnt(2)
	global_store_dwordx4 v165, v[116:119], s[26:27]
	s_waitcnt lgkmcnt(1)
	global_store_dwordx4 v166, v[120:123], s[26:27]
	s_waitcnt lgkmcnt(0)
	global_store_dwordx4 v167, v[124:127], s[26:27]
; __device__ __forceinline__ int crow(int r, int hi) { return (r & 3) + 8 * (r >> 2) + 4 * hi; }
; __device__ __forceinline__ int v_st(int k, int c) { const int kk = (k & ~0xC) | ((k & 4) << 1) | ((k & 8) >> 1); return ((kk >> 3) * 4 + (c >> 5)) * 512 + ((kk & 7) * 32 + (c & 31)) * 2; }
; __device__ __forceinline__ float bf2f(short s) { return __uint_as_float(((unsigned)(unsigned short)s) << 16); }
; __device__ __forceinline__ float bf2f(u16 u) { return __uint_as_float((unsigned)u << 16); }
; #define OPAQUE_TID(name) int name = MK_TID; asm volatile("" : "+v"(name))
; __device__ __forceinline__ void scan_unit(const int unit, const Args& a, unsigned char* lds, const int mk_wid) {
;     ...
;           const bf16x8 af = *(const bf16x8*)(lds + L_LR + (tt * 32 + r32) * 32 + hi * 16);
;           const f32x16 z = __builtin_amdgcn_mfma_f32_32x32x16_bf16(af, upf, f32x16{}, 0, 0, 0);
;           float* lw = las + (tt * 32 + 4 * hi) * 128 + ct * 32 + r32;
; #pragma unroll
;           for (int r = 0; r < 16; ++r) { const float zz = z[r] + biasc;
;               lw[crow(r, 0) * 128] = (fminf(zz, 0.f) - __builtin_amdgcn_logf(1.f + __builtin_amdgcn_exp2f(-1.4426950408889634f * fabsf(zz))) * 0.6931471805599453f) * (1.f / 16.f); } }
;         __syncthreads();
;         { OPAQUE_TID(t_); const int c = t_ & 127, g = t_ >> 7;
;           float bl[16]; float run = 0.f;
;           { const float* lp = las + (g * 16) * 128 + c;
; #pragma unroll
;             for (int ii = 0; ii < 16; ++ii) { run += lp[ii * 128]; bl[ii] = run; } }
;           gs[g * 128 + c] = run;
;           __syncthreads();
;           const float g0 = gs[c], g1 = gs[128 + c], g2 = gs[256 + c], g3 = gs[384 + c];
;           const float off = (g > 0 ? g0 : 0.f) + (g > 1 ? g1 : 0.f) + (g > 2 ? g2 : 0.f);
;           const float btot = (g0 + g1) + (g2 + g3);
;           const float dlc = __builtin_amdgcn_exp2f(btot * 1.4426950408889634f);
;           if (g == 0) dl[c] = dlc;
;           u16* qcol = qe + (g * 16) * QP + c; u16* kcol = ke + (g * 16) * QP + c; unsigned char* kdb = lds + L_KD + v_st(g * 16, c);
; #pragma unroll
;           for (int ii = 0; ii < 16; ++ii) { const float bb = bl[ii] + off;
;               const float qf = bf2f(qcol[ii * QP]), kf = bf2f(kcol[ii * QP]);
;               const float e = __builtin_amdgcn_exp2f(bb * 1.4426950408889634f), ker = kf * __builtin_amdgcn_rcpf(e);
.Lscan_noflush:
	ds_write2st64_b32 v80, v64, v65 offset1:2
	ds_write2st64_b32 v80, v66, v67 offset0:4 offset1:6
	ds_write2st64_b32 v80, v68, v69 offset0:16 offset1:18
	ds_write2st64_b32 v80, v70, v71 offset0:20 offset1:22
	v_pk_add_f32 v[72:73], v[72:73], v[156:157] op_sel_hi:[1,0]
	v_pk_add_f32 v[74:75], v[74:75], v[156:157] op_sel_hi:[1,0]
	v_pk_add_f32 v[76:77], v[76:77], v[156:157] op_sel_hi:[1,0]
	v_pk_add_f32 v[78:79], v[78:79], v[156:157] op_sel_hi:[1,0]
	v_mul_f32_e64 v82, |v72|, s54
	v_mul_f32_e64 v83, |v73|, s54
	v_mul_f32_e64 v84, |v74|, s54
	v_mul_f32_e64 v85, |v75|, s54
	v_mul_f32_e64 v86, |v76|, s54
	v_mul_f32_e64 v87, |v77|, s54
	v_mul_f32_e64 v88, |v78|, s54
	v_mul_f32_e64 v89, |v79|, s54
	v_exp_f32_e32 v82, v82
	v_exp_f32_e32 v83, v83
	v_exp_f32_e32 v84, v84
	v_exp_f32_e32 v85, v85
	v_exp_f32_e32 v86, v86
	v_exp_f32_e32 v87, v87
	v_exp_f32_e32 v88, v88
	v_exp_f32_e32 v89, v89
	v_pk_add_f32 v[82:83], v[82:83], s[96:97] op_sel_hi:[1,0]
	v_pk_add_f32 v[84:85], v[84:85], s[96:97] op_sel_hi:[1,0]
	v_pk_add_f32 v[86:87], v[86:87], s[96:97] op_sel_hi:[1,0]
	v_pk_add_f32 v[88:89], v[88:89], s[96:97] op_sel_hi:[1,0]
	v_log_f32_e32 v82, v82
	v_log_f32_e32 v83, v83
	v_log_f32_e32 v84, v84
	v_log_f32_e32 v85, v85
	v_log_f32_e32 v86, v86
	v_log_f32_e32 v87, v87
	v_log_f32_e32 v88, v88
	v_log_f32_e32 v89, v89
	v_min_f32_e32 v72, 0, v72
	v_min_f32_e32 v73, 0, v73
	v_min_f32_e32 v74, 0, v74
	v_min_f32_e32 v75, 0, v75
	v_min_f32_e32 v76, 0, v76
	v_min_f32_e32 v77, 0, v77
	v_min_f32_e32 v78, 0, v78
	v_min_f32_e32 v79, 0, v79
	v_pk_fma_f32 v[72:73], v[82:83], s[96:97], v[72:73] op_sel:[0,1,0] op_sel_hi:[1,1,1]
	v_pk_fma_f32 v[74:75], v[84:85], s[96:97], v[74:75] op_sel:[0,1,0] op_sel_hi:[1,1,1]
	v_pk_fma_f32 v[76:77], v[86:87], s[96:97], v[76:77] op_sel:[0,1,0] op_sel_hi:[1,1,1]
	v_pk_fma_f32 v[78:79], v[88:89], s[96:97], v[78:79] op_sel:[0,1,0] op_sel_hi:[1,1,1]
	v_pk_mul_f32 v[72:73], v[72:73], s[98:99] op_sel_hi:[1,0]
	v_pk_mul_f32 v[74:75], v[74:75], s[98:99] op_sel_hi:[1,0]
	v_pk_mul_f32 v[76:77], v[76:77], s[98:99] op_sel_hi:[1,0]
	v_pk_mul_f32 v[78:79], v[78:79], s[98:99] op_sel_hi:[1,0]
	ds_write2st64_b32 v80, v72, v73 offset0:32 offset1:34
	ds_write2st64_b32 v80, v74, v75 offset0:36 offset1:38
	ds_write2st64_b32 v80, v76, v77 offset0:48 offset1:50
	ds_write2st64_b32 v80, v78, v79 offset0:52 offset1:54
	v_pk_add_f32 v[82:83], v[64:65], v[66:67]
	v_pk_add_f32 v[84:85], v[68:69], v[70:71]
	v_pk_add_f32 v[86:87], v[72:73], v[74:75]
	v_pk_add_f32 v[88:89], v[76:77], v[78:79]
	v_add_f32_e32 v82, v82, v83
	v_add_f32_e32 v84, v84, v85
	v_add_f32_e32 v86, v86, v87
	v_add_f32_e32 v88, v88, v89
	ds_write2st64_b32 v169, v82, v84 offset1:4
	ds_write2st64_b32 v169, v86, v88 offset0:8 offset1:12
	s_waitcnt lgkmcnt(0)
	s_barrier
	v_mbcnt_lo_u32_b32 v64, -1, 0
	v_mbcnt_hi_u32_b32 v64, -1, v64
	s_lshl_b32 s96, s70, 12
	s_add_i32 s96, s96, s9
	v_lshl_add_u32 v65, v64, 3, s96
	v_lshlrev_b32_e32 v67, 3, v64
	v_add_u32_e32 v67, 0x20000, v67
	ds_read2st64_b64 v[186:189], v67 offset1:1
	ds_read2st64_b64 v[190:193], v67 offset0:2 offset1:3
	ds_read2st64_b64 v[194:197], v67 offset0:4 offset1:5
	ds_read2st64_b64 v[198:201], v67 offset0:6 offset1:7
	ds_read2st64_b64 v[202:205], v67 offset0:8 offset1:9
	ds_read2st64_b64 v[206:209], v67 offset0:10 offset1:11
	ds_read2st64_b64 v[210:213], v67 offset0:12 offset1:13
	ds_read2st64_b64 v[214:217], v67 offset0:14 offset1:15
	ds_read2st64_b64 v[170:173], v65 offset1:1
	ds_read2st64_b64 v[174:177], v65 offset0:2 offset1:3
	ds_read2st64_b64 v[178:181], v65 offset0:4 offset1:5
	ds_read2st64_b64 v[182:185], v65 offset0:6 offset1:7
	s_waitcnt lgkmcnt(4)
	v_pk_add_f32 v[72:73], v[186:187], v[188:189]
	v_pk_add_f32 v[74:75], v[190:191], v[192:193]
	v_pk_add_f32 v[76:77], v[194:195], v[196:197]
	v_pk_add_f32 v[78:79], v[198:199], v[200:201]
	v_pk_add_f32 v[80:81], v[202:203], v[204:205]
	v_pk_add_f32 v[82:83], v[206:207], v[208:209]
	v_pk_add_f32 v[84:85], v[210:211], v[212:213]
	v_pk_add_f32 v[86:87], v[214:215], v[216:217]
	v_pk_mul_f32 v[88:89], v[238:239], v[72:73] op_sel:[0,0] op_sel_hi:[0,1]
	v_pk_fma_f32 v[88:89], v[238:239], v[74:75], v[88:89] op_sel:[1,0,0] op_sel_hi:[1,1,1]
	v_pk_fma_f32 v[88:89], v[240:241], v[76:77], v[88:89] op_sel:[0,0,0] op_sel_hi:[0,1,1]
	v_pk_fma_f32 v[88:89], v[240:241], v[78:79], v[88:89] op_sel:[1,0,0] op_sel_hi:[1,1,1]
	v_pk_fma_f32 v[88:89], v[242:243], v[80:81], v[88:89] op_sel:[0,0,0] op_sel_hi:[0,1,1]
	v_pk_fma_f32 v[88:89], v[242:243], v[82:83], v[88:89] op_sel:[1,0,0] op_sel_hi:[1,1,1]
	v_pk_fma_f32 v[88:89], v[244:245], v[84:85], v[88:89] op_sel:[0,0,0] op_sel_hi:[0,1,1]
	v_pk_add_f32 v[90:91], v[72:73], v[74:75]
	v_pk_add_f32 v[90:91], v[90:91], v[76:77]
	v_pk_add_f32 v[90:91], v[90:91], v[78:79]
	v_pk_add_f32 v[90:91], v[90:91], v[80:81]
	v_pk_add_f32 v[90:91], v[90:91], v[82:83]
	v_pk_add_f32 v[90:91], v[90:91], v[84:85]
	v_pk_add_f32 v[90:91], v[90:91], v[86:87]
	v_mov_b64_e32 v[92:93], v[90:91]
	v_exp_f32_e32 v92, v92
	v_exp_f32_e32 v93, v93
	s_waitcnt lgkmcnt(0)
	v_pk_add_f32 v[170:171], v[170:171], v[88:89]
	v_pk_add_f32 v[172:173], v[172:173], v[170:171]
	v_pk_add_f32 v[174:175], v[174:175], v[172:173]
	v_pk_add_f32 v[176:177], v[176:177], v[174:175]
	v_pk_add_f32 v[178:179], v[178:179], v[176:177]
	v_pk_add_f32 v[180:181], v[180:181], v[178:179]
	v_pk_add_f32 v[182:183], v[182:183], v[180:181]
	v_pk_add_f32 v[184:185], v[184:185], v[182:183]
	v_exp_f32_e32 v170, v170
	v_exp_f32_e32 v171, v171
	v_exp_f32_e32 v172, v172
	v_exp_f32_e32 v173, v173
	v_exp_f32_e32 v174, v174
	v_exp_f32_e32 v175, v175
	v_exp_f32_e32 v176, v176
	v_exp_f32_e32 v177, v177
	v_exp_f32_e32 v178, v178
	v_exp_f32_e32 v179, v179
	v_exp_f32_e32 v180, v180
	v_exp_f32_e32 v181, v181
	v_exp_f32_e32 v182, v182
	v_exp_f32_e32 v183, v183
	v_exp_f32_e32 v184, v184
	v_exp_f32_e32 v185, v185
	v_rcp_f32_e32 v186, v170
	v_rcp_f32_e32 v187, v171
	v_rcp_f32_e32 v188, v172
	v_rcp_f32_e32 v189, v173
	v_rcp_f32_e32 v190, v174
	v_rcp_f32_e32 v191, v175
	v_rcp_f32_e32 v192, v176
	v_rcp_f32_e32 v193, v177
	v_rcp_f32_e32 v194, v178
	v_rcp_f32_e32 v195, v179
	v_rcp_f32_e32 v196, v180
	v_rcp_f32_e32 v197, v181
	v_rcp_f32_e32 v198, v182
	v_rcp_f32_e32 v199, v183
	v_rcp_f32_e32 v200, v184
	v_rcp_f32_e32 v201, v185
	s_mov_b32 s96, 0x3db504f3
	s_mov_b32 s97, s96
	v_pk_mul_f32 v[170:171], v[170:171], s[96:97]
	v_pk_mul_f32 v[172:173], v[172:173], s[96:97]
	v_pk_mul_f32 v[174:175], v[174:175], s[96:97]
	v_pk_mul_f32 v[176:177], v[176:177], s[96:97]
	v_pk_mul_f32 v[178:179], v[178:179], s[96:97]
	v_pk_mul_f32 v[180:181], v[180:181], s[96:97]
	v_pk_mul_f32 v[182:183], v[182:183], s[96:97]
	v_pk_mul_f32 v[184:185], v[184:185], s[96:97]
	s_cmp_lg_u32 s70, 0
	s_cbranch_scc1 .Lscan_c2_nodl
	v_lshlrev_b32_e32 v70, 3, v64
	v_add_u32_e32 v70, 0x1fc00, v70
	ds_write_b64 v70, v[92:93]
